# sn2 + P5 load stages free of VALU: saddr-form LDS-DMA (SGPR base + VGPR offset) and precomputed fragment read bases
# speedup vs baseline: 1.0066x; 1.0054x over previous
.LBB0_870:
	s_andn2_b64 vcc, exec, s[10:11]
	s_cbranch_vccnz .LBB0_873
	s_add_u32 s34, s16, 0x40080
	s_addc_u32 s35, s17, 0
	s_add_u32 s21, s18, 0x100
	s_addc_u32 s23, s19, 0
	s_mov_b32 s52, 0
	v_add_u32_e32 v246, 0x10000, v140
	v_add_u32_e32 v247, 0x14000, v140
	v_add_u32_e32 v248, 0x18000, v140
	v_add_u32_e32 v249, 0x1c000, v140
.LBB0_872:
	s_add_i32 s77, s52, 2
	s_add_u32 s50, s34, 0xfffc0080
	s_addc_u32 s51, s35, -1
	s_cmp_eq_u32 s70, s52
	s_cselect_b32 s52, s30, s21
	s_cselect_b32 s55, s29, s51
	s_cselect_b32 s54, s28, s50
	s_cselect_b32 s53, s31, s23
	ds_read_b128 v[150:153], v246
	ds_read_b128 v[154:157], v246 offset:1024
	ds_read_b128 v[158:161], v246 offset:2048
	ds_read_b128 v[162:165], v246 offset:3072
	ds_read_b128 v[166:169], v247
	ds_read_b128 v[170:173], v247 offset:1024
	ds_read_b128 v[174:177], v247 offset:2048
	ds_read_b128 v[178:181], v247 offset:3072
	ds_read_b128 v[182:185], v149
	ds_read_b128 v[186:189], v149 offset:1024
	ds_read_b128 v[190:193], v149 offset:2048
	ds_read_b128 v[194:197], v149 offset:3072
	ds_read_b128 v[198:201], v149 offset:4096
	ds_read_b128 v[202:205], v149 offset:5120
	ds_read_b128 v[206:209], v149 offset:6144
	ds_read_b128 v[210:213], v149 offset:7168
	s_add_i32 m0, s60, 0xc000
	s_nop 0
	global_load_lds_dwordx4 v132, s[34:35]
	s_add_i32 m0, s60, 0xe000
	s_nop 0
	global_load_lds_dwordx4 v134, s[34:35]
	s_waitcnt vmcnt(8)
	s_waitcnt lgkmcnt(0)
	s_barrier
	v_mfma_f32_16x16x32_bf16 v[78:81], v[150:153], v[182:185], v[78:81]
	v_mfma_f32_16x16x32_bf16 v[78:81], v[154:157], v[186:189], v[78:81]
	v_mfma_f32_16x16x32_bf16 v[66:69], v[154:157], v[194:197], v[66:69]
	v_mfma_f32_16x16x32_bf16 v[66:69], v[150:153], v[190:193], v[66:69]
	v_mfma_f32_16x16x32_bf16 v[70:73], v[150:153], v[198:201], v[70:73]
	v_mfma_f32_16x16x32_bf16 v[70:73], v[154:157], v[202:205], v[70:73]
	v_mfma_f32_16x16x32_bf16 v[74:77], v[154:157], v[210:213], v[74:77]
	v_mfma_f32_16x16x32_bf16 v[74:77], v[150:153], v[206:209], v[74:77]
	v_mfma_f32_16x16x32_bf16 v[10:13], v[158:161], v[206:209], v[10:13]
	v_mfma_f32_16x16x32_bf16 v[10:13], v[162:165], v[210:213], v[10:13]
	v_mfma_f32_16x16x32_bf16 v[6:9], v[162:165], v[202:205], v[6:9]
	v_mfma_f32_16x16x32_bf16 v[6:9], v[158:161], v[198:201], v[6:9]
	v_mfma_f32_16x16x32_bf16 v[2:5], v[158:161], v[190:193], v[2:5]
	v_mfma_f32_16x16x32_bf16 v[2:5], v[162:165], v[194:197], v[2:5]
	v_mfma_f32_16x16x32_bf16 v[14:17], v[162:165], v[186:189], v[14:17]
	v_mfma_f32_16x16x32_bf16 v[14:17], v[158:161], v[182:185], v[14:17]
	v_mfma_f32_16x16x32_bf16 v[98:101], v[166:169], v[182:185], v[98:101]
	v_mfma_f32_16x16x32_bf16 v[98:101], v[170:173], v[186:189], v[98:101]
	v_mfma_f32_16x16x32_bf16 v[82:85], v[170:173], v[194:197], v[82:85]
	v_mfma_f32_16x16x32_bf16 v[82:85], v[166:169], v[190:193], v[82:85]
	v_mfma_f32_16x16x32_bf16 v[86:89], v[166:169], v[198:201], v[86:89]
	v_mfma_f32_16x16x32_bf16 v[86:89], v[170:173], v[202:205], v[86:89]
	v_mfma_f32_16x16x32_bf16 v[94:97], v[170:173], v[210:213], v[94:97]
	v_mfma_f32_16x16x32_bf16 v[94:97], v[166:169], v[206:209], v[94:97]
	v_mfma_f32_16x16x32_bf16 v[30:33], v[174:177], v[206:209], v[30:33]
	v_mfma_f32_16x16x32_bf16 v[30:33], v[178:181], v[210:213], v[30:33]
	v_mfma_f32_16x16x32_bf16 v[22:25], v[178:181], v[202:205], v[22:25]
	v_mfma_f32_16x16x32_bf16 v[22:25], v[174:177], v[198:201], v[22:25]
	v_mfma_f32_16x16x32_bf16 v[18:21], v[174:177], v[190:193], v[18:21]
	v_mfma_f32_16x16x32_bf16 v[18:21], v[178:181], v[194:197], v[18:21]
	v_mfma_f32_16x16x32_bf16 v[34:37], v[178:181], v[186:189], v[34:37]
	v_mfma_f32_16x16x32_bf16 v[34:37], v[174:177], v[182:185], v[34:37]
	s_barrier
	ds_read_b128 v[182:185], v149 offset:16384
	ds_read_b128 v[186:189], v149 offset:17408
	ds_read_b128 v[190:193], v149 offset:18432
	ds_read_b128 v[194:197], v149 offset:19456
	ds_read_b128 v[198:201], v149 offset:20480
	ds_read_b128 v[202:205], v149 offset:21504
	ds_read_b128 v[206:209], v149 offset:22528
	ds_read_b128 v[210:213], v149 offset:23552
	s_add_i32 s50, s73, s15
	s_mov_b32 m0, s50
	s_nop 0
	global_load_lds_dwordx4 v228, s[52:53]
	s_add_i32 m0, s50, 0x2000
	s_add_u32 s50, s52, 0x40000
	s_addc_u32 s51, s53, 0
	s_add_i32 s78, s74, s15
	global_load_lds_dwordx4 v232, s[52:53]
	s_mov_b32 m0, s78
	s_nop 0
	global_load_lds_dwordx4 v228, s[50:51]
	s_add_i32 m0, s78, 0x2000
	s_nop 0
	global_load_lds_dwordx4 v232, s[50:51]
	s_mov_b32 m0, s60
	s_nop 0
	global_load_lds_dwordx4 v226, s[54:55]
	s_mov_b32 m0, s61
	s_nop 0
	global_load_lds_dwordx4 v230, s[54:55]
	s_waitcnt vmcnt(8)
	s_waitcnt lgkmcnt(0)
	s_barrier
	v_mfma_f32_16x16x32_bf16 v[90:93], v[150:153], v[182:185], v[90:93]
	v_mfma_f32_16x16x32_bf16 v[90:93], v[154:157], v[186:189], v[90:93]
	v_mfma_f32_16x16x32_bf16 v[102:105], v[154:157], v[194:197], v[102:105]
	v_mfma_f32_16x16x32_bf16 v[102:105], v[150:153], v[190:193], v[102:105]
	v_mfma_f32_16x16x32_bf16 v[106:109], v[150:153], v[198:201], v[106:109]
	v_mfma_f32_16x16x32_bf16 v[106:109], v[154:157], v[202:205], v[106:109]
	v_mfma_f32_16x16x32_bf16 v[110:113], v[154:157], v[210:213], v[110:113]
	v_mfma_f32_16x16x32_bf16 v[110:113], v[150:153], v[206:209], v[110:113]
	v_mfma_f32_16x16x32_bf16 v[46:49], v[158:161], v[206:209], v[46:49]
	v_mfma_f32_16x16x32_bf16 v[46:49], v[162:165], v[210:213], v[46:49]
	v_mfma_f32_16x16x32_bf16 v[42:45], v[162:165], v[202:205], v[42:45]
	v_mfma_f32_16x16x32_bf16 v[42:45], v[158:161], v[198:201], v[42:45]
	v_mfma_f32_16x16x32_bf16 v[38:41], v[158:161], v[190:193], v[38:41]
	v_mfma_f32_16x16x32_bf16 v[38:41], v[162:165], v[194:197], v[38:41]
	v_mfma_f32_16x16x32_bf16 v[26:29], v[162:165], v[186:189], v[26:29]
	v_mfma_f32_16x16x32_bf16 v[26:29], v[158:161], v[182:185], v[26:29]
	v_mfma_f32_16x16x32_bf16 v[114:117], v[166:169], v[182:185], v[114:117]
	v_mfma_f32_16x16x32_bf16 v[114:117], v[170:173], v[186:189], v[114:117]
	v_mfma_f32_16x16x32_bf16 v[118:121], v[170:173], v[194:197], v[118:121]
	v_mfma_f32_16x16x32_bf16 v[118:121], v[166:169], v[190:193], v[118:121]
	v_mfma_f32_16x16x32_bf16 v[122:125], v[166:169], v[198:201], v[122:125]
	v_mfma_f32_16x16x32_bf16 v[122:125], v[170:173], v[202:205], v[122:125]
	v_mfma_f32_16x16x32_bf16 v[126:129], v[170:173], v[210:213], v[126:129]
	v_mfma_f32_16x16x32_bf16 v[126:129], v[166:169], v[206:209], v[126:129]
	v_mfma_f32_16x16x32_bf16 v[62:65], v[174:177], v[206:209], v[62:65]
	v_mfma_f32_16x16x32_bf16 v[62:65], v[178:181], v[210:213], v[62:65]
	v_mfma_f32_16x16x32_bf16 v[58:61], v[178:181], v[202:205], v[58:61]
	v_mfma_f32_16x16x32_bf16 v[58:61], v[174:177], v[198:201], v[58:61]
	v_mfma_f32_16x16x32_bf16 v[54:57], v[174:177], v[190:193], v[54:57]
	v_mfma_f32_16x16x32_bf16 v[54:57], v[178:181], v[194:197], v[54:57]
	v_mfma_f32_16x16x32_bf16 v[50:53], v[178:181], v[186:189], v[50:53]
	v_mfma_f32_16x16x32_bf16 v[50:53], v[174:177], v[182:185], v[50:53]
	s_barrier
	s_add_i32 s78, 0, 0x18000
	s_add_i32 s79, 0, 0x1c000
	ds_read_b128 v[150:153], v248
	ds_read_b128 v[154:157], v248 offset:1024
	ds_read_b128 v[158:161], v248 offset:2048
	ds_read_b128 v[162:165], v248 offset:3072
	ds_read_b128 v[166:169], v249
	ds_read_b128 v[170:173], v249 offset:1024
	ds_read_b128 v[174:177], v249 offset:2048
	ds_read_b128 v[178:181], v249 offset:3072
	ds_read_b128 v[182:185], v149 offset:32768
	ds_read_b128 v[186:189], v149 offset:33792
	ds_read_b128 v[190:193], v149 offset:34816
	ds_read_b128 v[194:197], v149 offset:35840
	ds_read_b128 v[198:201], v149 offset:36864
	ds_read_b128 v[202:205], v149 offset:37888
	ds_read_b128 v[206:209], v149 offset:38912
	ds_read_b128 v[210:213], v149 offset:39936
	s_add_u32 s50, s54, 0x40000
	s_addc_u32 s51, s55, 0
	s_mov_b32 m0, s62
	s_nop 0
	global_load_lds_dwordx4 v226, s[50:51]
	s_mov_b32 m0, s63
	s_nop 0
	global_load_lds_dwordx4 v230, s[50:51]
	s_waitcnt vmcnt(8)
	s_waitcnt lgkmcnt(0)
	s_barrier
	v_mfma_f32_16x16x32_bf16 v[78:81], v[150:153], v[182:185], v[78:81]
	v_mfma_f32_16x16x32_bf16 v[78:81], v[154:157], v[186:189], v[78:81]
	v_mfma_f32_16x16x32_bf16 v[66:69], v[154:157], v[194:197], v[66:69]
	v_mfma_f32_16x16x32_bf16 v[66:69], v[150:153], v[190:193], v[66:69]
	v_mfma_f32_16x16x32_bf16 v[70:73], v[150:153], v[198:201], v[70:73]
	v_mfma_f32_16x16x32_bf16 v[70:73], v[154:157], v[202:205], v[70:73]
	v_mfma_f32_16x16x32_bf16 v[74:77], v[154:157], v[210:213], v[74:77]
	v_mfma_f32_16x16x32_bf16 v[74:77], v[150:153], v[206:209], v[74:77]
	v_mfma_f32_16x16x32_bf16 v[10:13], v[158:161], v[206:209], v[10:13]
	v_mfma_f32_16x16x32_bf16 v[10:13], v[162:165], v[210:213], v[10:13]
	v_mfma_f32_16x16x32_bf16 v[6:9], v[162:165], v[202:205], v[6:9]
	v_mfma_f32_16x16x32_bf16 v[6:9], v[158:161], v[198:201], v[6:9]
	v_mfma_f32_16x16x32_bf16 v[2:5], v[158:161], v[190:193], v[2:5]
	v_mfma_f32_16x16x32_bf16 v[2:5], v[162:165], v[194:197], v[2:5]
	v_mfma_f32_16x16x32_bf16 v[14:17], v[162:165], v[186:189], v[14:17]
	v_mfma_f32_16x16x32_bf16 v[14:17], v[158:161], v[182:185], v[14:17]
	v_mfma_f32_16x16x32_bf16 v[98:101], v[166:169], v[182:185], v[98:101]
	v_mfma_f32_16x16x32_bf16 v[98:101], v[170:173], v[186:189], v[98:101]
	v_mfma_f32_16x16x32_bf16 v[82:85], v[170:173], v[194:197], v[82:85]
	v_mfma_f32_16x16x32_bf16 v[82:85], v[166:169], v[190:193], v[82:85]
	v_mfma_f32_16x16x32_bf16 v[86:89], v[166:169], v[198:201], v[86:89]
	v_mfma_f32_16x16x32_bf16 v[86:89], v[170:173], v[202:205], v[86:89]
	v_mfma_f32_16x16x32_bf16 v[94:97], v[170:173], v[210:213], v[94:97]
	v_mfma_f32_16x16x32_bf16 v[94:97], v[166:169], v[206:209], v[94:97]
	v_mfma_f32_16x16x32_bf16 v[30:33], v[174:177], v[206:209], v[30:33]
	v_mfma_f32_16x16x32_bf16 v[30:33], v[178:181], v[210:213], v[30:33]
	v_mfma_f32_16x16x32_bf16 v[22:25], v[178:181], v[202:205], v[22:25]
	v_mfma_f32_16x16x32_bf16 v[22:25], v[174:177], v[198:201], v[22:25]
	v_mfma_f32_16x16x32_bf16 v[18:21], v[174:177], v[190:193], v[18:21]
	v_mfma_f32_16x16x32_bf16 v[18:21], v[178:181], v[194:197], v[18:21]
	v_mfma_f32_16x16x32_bf16 v[34:37], v[178:181], v[186:189], v[34:37]
	v_mfma_f32_16x16x32_bf16 v[34:37], v[174:177], v[182:185], v[34:37]
	s_barrier
	ds_read_b128 v[182:185], v149 offset:49152
	ds_read_b128 v[186:189], v149 offset:50176
	ds_read_b128 v[190:193], v149 offset:51200
	ds_read_b128 v[194:197], v149 offset:52224
	ds_read_b128 v[198:201], v149 offset:53248
	ds_read_b128 v[202:205], v149 offset:54272
	ds_read_b128 v[206:209], v149 offset:55296
	ds_read_b128 v[210:213], v149 offset:56320
	s_add_u32 s98, s52, 0x80
	s_addc_u32 s99, s53, 0
	s_add_u32 s100, s54, 0x80
	s_addc_u32 s101, s55, 0
	s_add_i32 s50, s78, s15
	s_mov_b32 m0, s50
	s_nop 0
	global_load_lds_dwordx4 v228, s[98:99]
	s_add_i32 m0, s50, 0x2000
	s_add_u32 s50, s52, 0x40080
	s_addc_u32 s51, s53, 0
	global_load_lds_dwordx4 v232, s[98:99]
	s_add_i32 s52, s79, s15
	s_mov_b32 m0, s52
	s_nop 0
	global_load_lds_dwordx4 v228, s[50:51]
	s_add_i32 m0, s52, 0x2000
	s_nop 0
	global_load_lds_dwordx4 v232, s[50:51]
	s_mov_b32 m0, s68
	s_nop 0
	global_load_lds_dwordx4 v226, s[100:101]
	s_mov_b32 m0, s69
	s_nop 0
	global_load_lds_dwordx4 v230, s[100:101]
	s_waitcnt vmcnt(8)
	s_waitcnt lgkmcnt(0)
	s_barrier
	v_mfma_f32_16x16x32_bf16 v[90:93], v[150:153], v[182:185], v[90:93]
	v_mfma_f32_16x16x32_bf16 v[90:93], v[154:157], v[186:189], v[90:93]
	v_mfma_f32_16x16x32_bf16 v[102:105], v[154:157], v[194:197], v[102:105]
	v_mfma_f32_16x16x32_bf16 v[102:105], v[150:153], v[190:193], v[102:105]
	v_mfma_f32_16x16x32_bf16 v[106:109], v[150:153], v[198:201], v[106:109]
	v_mfma_f32_16x16x32_bf16 v[106:109], v[154:157], v[202:205], v[106:109]
	v_mfma_f32_16x16x32_bf16 v[110:113], v[154:157], v[210:213], v[110:113]
	v_mfma_f32_16x16x32_bf16 v[110:113], v[150:153], v[206:209], v[110:113]
	v_mfma_f32_16x16x32_bf16 v[46:49], v[158:161], v[206:209], v[46:49]
	v_mfma_f32_16x16x32_bf16 v[46:49], v[162:165], v[210:213], v[46:49]
	v_mfma_f32_16x16x32_bf16 v[42:45], v[162:165], v[202:205], v[42:45]
	v_mfma_f32_16x16x32_bf16 v[42:45], v[158:161], v[198:201], v[42:45]
	v_mfma_f32_16x16x32_bf16 v[38:41], v[158:161], v[190:193], v[38:41]
	v_mfma_f32_16x16x32_bf16 v[38:41], v[162:165], v[194:197], v[38:41]
	v_mfma_f32_16x16x32_bf16 v[26:29], v[162:165], v[186:189], v[26:29]
	v_mfma_f32_16x16x32_bf16 v[26:29], v[158:161], v[182:185], v[26:29]
	v_mfma_f32_16x16x32_bf16 v[114:117], v[166:169], v[182:185], v[114:117]
	v_mfma_f32_16x16x32_bf16 v[114:117], v[170:173], v[186:189], v[114:117]
	v_mfma_f32_16x16x32_bf16 v[118:121], v[170:173], v[194:197], v[118:121]
	v_mfma_f32_16x16x32_bf16 v[118:121], v[166:169], v[190:193], v[118:121]
	v_mfma_f32_16x16x32_bf16 v[122:125], v[166:169], v[198:201], v[122:125]
	v_mfma_f32_16x16x32_bf16 v[122:125], v[170:173], v[202:205], v[122:125]
	v_mfma_f32_16x16x32_bf16 v[126:129], v[170:173], v[210:213], v[126:129]
	v_mfma_f32_16x16x32_bf16 v[126:129], v[166:169], v[206:209], v[126:129]
	v_mfma_f32_16x16x32_bf16 v[62:65], v[174:177], v[206:209], v[62:65]
	v_mfma_f32_16x16x32_bf16 v[62:65], v[178:181], v[210:213], v[62:65]
	v_mfma_f32_16x16x32_bf16 v[58:61], v[178:181], v[202:205], v[58:61]
	v_mfma_f32_16x16x32_bf16 v[58:61], v[174:177], v[198:201], v[58:61]
	v_mfma_f32_16x16x32_bf16 v[54:57], v[174:177], v[190:193], v[54:57]
	v_mfma_f32_16x16x32_bf16 v[54:57], v[178:181], v[194:197], v[54:57]
	v_mfma_f32_16x16x32_bf16 v[50:53], v[178:181], v[186:189], v[50:53]
	v_mfma_f32_16x16x32_bf16 v[50:53], v[174:177], v[182:185], v[50:53]
	s_barrier
	s_add_u32 s34, s34, 0x100
	s_addc_u32 s35, s35, 0
	s_add_u32 s21, s21, 0x100
	s_addc_u32 s23, s23, 0
	s_cmp_ge_i32 s77, s66
	s_mov_b32 s52, s77
	s_cbranch_scc0 .LBB0_872

	.amdhsa_kernel _Z10hybrid_fwd4Args
		.amdhsa_group_segment_fixed_size 0
		.amdhsa_private_segment_fixed_size 0
		.amdhsa_kernarg_size 512
		.amdhsa_user_sgpr_count 2
		.amdhsa_user_sgpr_dispatch_ptr 0
		.amdhsa_user_sgpr_queue_ptr 0
		.amdhsa_user_sgpr_kernarg_segment_ptr 1
		.amdhsa_user_sgpr_dispatch_id 0
		.amdhsa_user_sgpr_kernarg_preload_length 0
		.amdhsa_user_sgpr_kernarg_preload_offset 0
		.amdhsa_user_sgpr_private_segment_size 0
		.amdhsa_uses_dynamic_stack 0
		.amdhsa_enable_private_segment 0
		.amdhsa_system_sgpr_workgroup_id_x 1
		.amdhsa_system_sgpr_workgroup_id_y 0
		.amdhsa_system_sgpr_workgroup_id_z 0
		.amdhsa_system_sgpr_workgroup_info 0
		.amdhsa_system_vgpr_workitem_id 0
		.amdhsa_next_free_vgpr 256
		.amdhsa_next_free_sgpr 102
		.amdhsa_accum_offset 256
		.amdhsa_reserve_vcc 1
		.amdhsa_float_round_mode_32 0
		.amdhsa_float_round_mode_16_64 0
		.amdhsa_float_denorm_mode_32 3
		.amdhsa_float_denorm_mode_16_64 3
		.amdhsa_dx10_clamp 1
		.amdhsa_ieee_mode 1
		.amdhsa_fp16_overflow 0
		.amdhsa_tg_split 0
		.amdhsa_exception_fp_ieee_invalid_op 0
		.amdhsa_exception_fp_denorm_src 0
		.amdhsa_exception_fp_ieee_div_zero 0
		.amdhsa_exception_fp_ieee_overflow 0
		.amdhsa_exception_fp_ieee_underflow 0
		.amdhsa_exception_fp_ieee_inexact 0
		.amdhsa_exception_int_div_zero 0
	.end_amdhsa_kernel

amdhsa.kernels:
  - .agpr_count:     0
    .args:
      - .offset:         0
        .size:           256
        .value_kind:     by_value
      - .offset:         256
        .size:           4
        .value_kind:     hidden_block_count_x
      - .offset:         260
        .size:           4
        .value_kind:     hidden_block_count_y
      - .offset:         264
        .size:           4
        .value_kind:     hidden_block_count_z
      - .offset:         268
        .size:           2
        .value_kind:     hidden_group_size_x
      - .offset:         270
        .size:           2
        .value_kind:     hidden_group_size_y
      - .offset:         272
        .size:           2
        .value_kind:     hidden_group_size_z
      - .offset:         274
        .size:           2
        .value_kind:     hidden_remainder_x
      - .offset:         276
        .size:           2
        .value_kind:     hidden_remainder_y
      - .offset:         278
        .size:           2
        .value_kind:     hidden_remainder_z
      - .offset:         296
        .size:           8
        .value_kind:     hidden_global_offset_x
      - .offset:         304
        .size:           8
        .value_kind:     hidden_global_offset_y
      - .offset:         312
        .size:           8
        .value_kind:     hidden_global_offset_z
      - .offset:         320
        .size:           2
        .value_kind:     hidden_grid_dims
      - .offset:         376
        .size:           4
        .value_kind:     hidden_dynamic_lds_size
    .group_segment_fixed_size: 0
    .kernarg_segment_align: 8
    .kernarg_segment_size: 512
    .language:       OpenCL C
    .language_version:
      - 2
      - 0
    .max_flat_workgroup_size: 512
    .name:           _Z10hybrid_fwd4Args
    .private_segment_fixed_size: 0
    .sgpr_count:     108
    .sgpr_spill_count: 2
    .symbol:         _Z10hybrid_fwd4Args.kd
    .uniform_work_group_size: 1
    .uses_dynamic_stack: false
    .vgpr_count:     256
    .vgpr_spill_count: 0
    .wavefront_size: 64
